# static s_setprio 1 for waves 0-3 at the attention phase entry (priority raise for one wave half, guide 7.4)
# baseline (speedup 1.0000x reference)
; __global__ void __launch_bounds__(512, 2) mega(Params p) {
;     ...
;     {
;       const int nself = (kind == 0) ? 1024 : 2048, total = nself + 512;
;       const u16* mgb = (kind == 0) ? MG : Pb;
;       const int ldmg = (kind == 0) ? 4096 : (kind == 1 ? 7808 : 6656);
;       const int mqcol = (kind == 0) ? 0 : (kind == 1 ? 3664 : 2560);
;       const int gatecol = (kind == 0) ? 1024 : (kind == 1 ? 4688 : 3584);
;       const u16* memkv = MEMKV + layer * 2048;
;       float* lut_all = (float*)(smem + LDS_LUT);
;       if (kind != 0) {
;         for (int i = tid; i < 32 * 129; i += 512) { const int h = i / 129, r = i - h * 129; lut_all[h * 132 + r] = LUT[r * 32 + h]; }
;       }
;       if (tid == 0) s_item[0] = atomicAdd(&CTR[layer], 1);
;       __syncthreads();
;       for (int par = 0;; par ^= 1) {
;         const int item = __builtin_amdgcn_readfirstlane(s_item[par]);
;         if (item >= total) break;
;         if (tid == 0) s_item[par ^ 1] = atomicAdd(&CTR[layer], 1);
.LBB0_1237:
	s_or_b64 exec, exec, s[0:1]
	s_or_b32 s23, s22, 0x200
	v_readlane_b32 s0, v254, 51
	s_cmp_lg_u32 s0, 1
	s_cselect_b64 s[66:67], -1, 0
	s_cmp_eq_u32 s0, 1
	s_movk_i32 s0, 0x1a00
	s_cselect_b32 s8, 0x1e80, s0
	s_movk_i32 s0, 0xe50
	s_cselect_b32 s9, s0, 0xa00
	s_movk_i32 s0, 0x1250
	s_cselect_b32 s10, s0, 0xe00
	v_readlane_b32 s0, v254, 52
	v_readlane_b32 s1, v254, 53
	s_and_b64 s[0:1], s[0:1], exec
	v_readlane_b32 s0, v254, 54
	s_cselect_b32 s24, 0x1000, s8
	s_cselect_b32 s8, 0, s9
	s_cselect_b32 s9, 0x400, s10
	v_readlane_b32 s1, v254, 55
	s_lshl_b32 s0, s0, 1
	s_add_u32 s59, s76, s0
	v_readlane_b32 s0, v254, 41
	v_readlane_b32 s1, v254, 42
	s_addc_u32 s65, s77, 0
	s_lshl_b64 s[0:1], s[0:1], 2
	v_readlane_b32 s10, v250, 48
	s_add_u32 s78, s10, s0
	v_readlane_b32 s0, v250, 49
	s_addc_u32 s79, s0, s1
	v_readlane_b32 s0, v254, 45
	v_readlane_b32 s1, v254, 46
	s_and_b64 s[0:1], s[0:1], exec
	s_mov_b32 s25, 0
	s_cselect_b32 s85, 32, 0
	s_lshl_b32 s72, s8, 1
	s_lshl_b32 s68, s9, 1
	v_readfirstlane_b32 s100, v179
	s_nop 3
	s_cmp_ge_u32 s100, 0x100
	s_cbranch_scc1 .Lprio_att_done
	s_setprio 1
.Lprio_att_done:
	s_waitcnt lgkmcnt(0)
	s_barrier
	s_branch .LBB0_1241
